# v6 + wi phase start de-serialised: RMS partial-sum loads issued first, prologue LDS-DMA issued before the 1/rms computation (one exposed latency instead of two)
# speedup vs baseline: 1.0033x; 1.0033x over previous
.LBB0_134:
	s_andn2_b64 vcc, exec, s[0:1]
	s_cbranch_vccnz .LBB0_203
	v_readlane_b32 s0, v252, 4
	s_nop 1
	v_writelane_b32 v252, s0, 4
	s_movk_i32 s0, 0x100
	v_cmp_gt_i32_e32 vcc, s0, v244
	s_and_saveexec_b64 s[100:101], vcc
	s_cbranch_execz .Lwi_rs_ld_done
	v_readlane_b32 s6, v252, 9
	s_nop 1
	v_add_u32_e32 v40, s6, v244
	s_waitcnt lgkmcnt(0)
	v_ashrrev_i32_e32 v41, 31, v40
	v_lshlrev_b64 v[40:41], 7, v[40:41]
	v_lshl_add_u64 v[68:69], s[96:97], 0, v[40:41]
	global_load_dwordx4 v[40:43], v[68:69], off
	global_load_dwordx4 v[44:47], v[68:69], off offset:16
	global_load_dwordx4 v[48:51], v[68:69], off offset:32
	global_load_dwordx4 v[52:55], v[68:69], off offset:48
	global_load_dwordx4 v[56:59], v[68:69], off offset:64
	global_load_dwordx4 v[60:63], v[68:69], off offset:80
	global_load_dwordx4 v[64:67], v[68:69], off offset:96
	s_nop 0
	global_load_dwordx4 v[68:71], v[68:69], off offset:112
.Lwi_rs_ld_done:
	s_or_b64 exec, exec, s[100:101]
	s_waitcnt lgkmcnt(0)
	v_mov_b32_e32 v5, v0
	s_nop 0
	v_readfirstlane_b32 s6, v5
	v_lshlrev_b32_e32 v2, 4, v5
	v_add_u32_e32 v6, 0x2000, v2
	v_ashrrev_i32_e32 v4, 31, v6
	v_lshrrev_b32_e32 v4, 22, v4
	v_add_u32_e32 v4, v6, v4
	v_ashrrev_i32_e32 v4, 10, v4
	v_mul_i32_i24_e32 v7, 0x400, v4
	v_sub_u32_e32 v6, v6, v7
	v_lshrrev_b32_e32 v7, 4, v6
	v_bitop3_b32 v7, v7, v6, 32 bitop3:0x6c
	v_ashrrev_i32_e32 v6, 31, v7
	v_lshrrev_b32_e32 v6, 26, v6
	v_add_u32_e32 v8, v7, v6
	v_lshlrev_b32_e32 v9, 3, v4
	s_mul_i32 s0, s77, 0x4200000
	v_readlane_b32 s1, v252, 10
	v_ashrrev_i32_e32 v6, 6, v8
	v_and_b32_e32 v9, -16, v9
	s_add_u32 s44, s1, s0
	v_readlane_b32 s0, v252, 11
	v_add_u32_e32 v9, v6, v9
	s_addc_u32 s45, s0, 0
	v_and_b32_e32 v10, 3, v6
	s_mov_b32 s0, 0x1ffffe0
	v_lshrrev_b32_e32 v11, 2, v9
	v_lshlrev_b32_e32 v12, 1, v9
	v_and_b32_e32 v8, 0xc0, v8
	v_and_or_b32 v10, v9, s0, v10
	v_and_b32_e32 v11, 4, v11
	v_and_b32_e32 v12, 24, v12
	v_sub_u32_e32 v7, v7, v8
	v_or3_b32 v10, v10, v11, v12
	v_lshlrev_b32_e32 v11, 5, v4
	v_ashrrev_i16_sdwa v7, v247, sext(v7) dst_sel:DWORD dst_unused:UNUSED_PAD src0_sel:DWORD src1_sel:BYTE_0
	v_and_b32_e32 v11, 32, v11
	v_bfe_i32 v7, v7, 0, 16
	v_add_lshl_u32 v8, v11, v7, 1
	v_lshl_add_u32 v132, v10, 7, v8
	v_lshl_add_u32 v134, v9, 12, v8
	v_bfe_i32 v8, v5, 27, 1
	v_lshrrev_b32_e32 v8, 22, v8
	v_add_u32_e32 v8, v2, v8
	v_and_b32_e32 v8, 0xfffffc00, v8
	v_sub_u32_e32 v2, v2, v8
	v_lshrrev_b32_e32 v8, 4, v2
	v_ashrrev_i32_e32 v9, 31, v5
	v_bitop3_b32 v2, v8, v2, 32 bitop3:0x6c
	v_lshrrev_b32_e32 v9, 26, v9
	v_ashrrev_i32_e32 v8, 31, v2
	v_add_u32_e32 v9, v5, v9
	v_lshrrev_b32_e32 v8, 26, v8
	v_ashrrev_i32_e32 v9, 6, v9
	v_add_u32_e32 v10, v2, v8
	v_lshlrev_b32_e32 v11, 3, v9
	v_ashrrev_i32_e32 v8, 6, v10
	v_and_b32_e32 v11, -16, v11
	v_add_u32_e32 v11, v8, v11
	v_and_b32_e32 v12, 3, v8
	v_lshrrev_b32_e32 v13, 2, v11
	v_lshlrev_b32_e32 v14, 1, v11
	v_and_b32_e32 v10, 0xc0, v10
	s_ashr_i32 s7, s6, 6
	v_and_or_b32 v12, v11, s0, v12
	v_and_b32_e32 v13, 4, v13
	v_and_b32_e32 v14, 24, v14
	v_sub_u32_e32 v2, v2, v10
	s_ashr_i32 s8, s6, 8
	s_lshl_b32 s46, s7, 10
	v_or3_b32 v12, v12, v13, v14
	v_lshlrev_b32_e32 v13, 5, v9
	v_ashrrev_i16_sdwa v2, v247, sext(v2) dst_sel:DWORD dst_unused:UNUSED_PAD src0_sel:DWORD src1_sel:BYTE_0
	v_readlane_b32 s0, v253, 34
	v_and_b32_e32 v13, 32, v13
	v_bfe_i32 v10, v2, 0, 16
	v_readlane_b32 s1, v253, 35
	s_add_u32 s34, s44, s0
	v_add_lshl_u32 v13, v13, v10, 1
	s_addc_u32 s35, s45, s1
	s_add_i32 s47, s46, 0
	v_lshl_add_u32 v2, v12, 7, v13
	s_add_i32 m0, s47, 0x10000
	v_lshl_add_u32 v136, v11, 12, v13
	global_load_lds_dwordx4 v2, s[34:35]
	s_add_i32 m0, s47, 0x12000
	s_add_u32 s0, s34, 0x4000
	global_load_lds_dwordx4 v132, s[34:35]
	s_addc_u32 s1, s35, 0
	s_add_i32 m0, s47, 0x14000
	s_add_i32 s48, s47, 0x2000
	global_load_lds_dwordx4 v2, s[0:1]
	s_add_i32 m0, s47, 0x16000
	s_add_i32 s49, s47, 0x4000
	global_load_lds_dwordx4 v132, s[0:1]
	v_readlane_b32 s0, v253, 38
	s_mov_b32 m0, s47
	v_readlane_b32 s1, v253, 39
	s_add_i32 s50, s47, 0x6000
	s_cmp_eq_u32 s8, 1
	s_nop 2
	global_load_lds_dwordx4 v136, s[0:1]
	s_mov_b32 m0, s48
	s_nop 0
	global_load_lds_dwordx4 v134, s[0:1]
	v_readlane_b32 s0, v253, 40
	s_mov_b32 m0, s49
	v_readlane_b32 s1, v253, 41
	s_nop 4
	global_load_lds_dwordx4 v136, s[0:1]
	s_mov_b32 m0, s50
	s_nop 0
	global_load_lds_dwordx4 v134, s[0:1]
	s_movk_i32 s0, 0x100
	v_cmp_gt_i32_e32 vcc, s0, v244
	s_and_saveexec_b64 s[0:1], vcc
	s_cbranch_execz .LBB0_137
	s_mov_b32 s6, 0xf800000
	s_waitcnt vmcnt(8)
	v_mov_b32_e32 v72, v40
	v_mov_b32_e32 v73, v44
	v_mov_b32_e32 v44, v41
	v_mov_b32_e32 v40, v42
	v_mov_b32_e32 v41, v46
	v_mov_b32_e32 v46, v43
	v_mov_b32_e32 v42, v49
	v_mov_b32_e32 v43, v50
	v_mov_b32_e32 v49, v51
	v_pk_add_f32 v[44:45], v[72:73], v[44:45]
	v_pk_add_f32 v[40:41], v[40:41], v[46:47]
	v_pk_add_f32 v[42:43], v[42:43], v[48:49]
	v_pk_add_f32 v[40:41], v[44:45], v[40:41]
	v_pk_add_f32 v[42:43], v[42:43], v[42:43] op_sel:[0,1] op_sel_hi:[1,0]
	v_add_f32_e32 v38, 0, v40
	v_add_f32_e32 v50, v52, v53
	v_add_f32_e32 v52, v54, v55
	v_mov_b32_e32 v55, v56
	v_mov_b32_e32 v51, v58
	v_mov_b32_e32 v53, v59
	v_mov_b32_e32 v43, v57
	v_add_f32_e32 v54, v38, v41
	v_mov_b32_e32 v58, v61
	v_mov_b32_e32 v59, v62
	v_mov_b32_e32 v61, v63
	v_pk_add_f32 v[46:47], v[50:51], v[52:53]
	v_pk_add_f32 v[40:41], v[54:55], v[42:43]
	v_pk_add_f32 v[48:49], v[58:59], v[60:61]
	v_pk_add_f32 v[40:41], v[40:41], v[46:47]
	v_pk_add_f32 v[44:45], v[48:49], v[48:49] op_sel:[0,1] op_sel_hi:[1,0]
	v_pk_add_f32 v[40:41], v[40:41], v[40:41] op_sel:[0,1] op_sel_hi:[1,0]
	v_add_f32_e32 v62, v64, v65
	v_add_f32_e32 v64, v66, v67
	v_mov_b32_e32 v63, v70
	v_mov_b32_e32 v65, v71
	v_mov_b32_e32 v45, v69
	v_mov_b32_e32 v41, v68
	v_pk_add_f32 v[50:51], v[62:63], v[64:65]
	v_pk_add_f32 v[40:41], v[40:41], v[44:45]
	s_nop 0
	v_pk_add_f32 v[40:41], v[40:41], v[50:51]
	s_nop 0
	v_add_f32_e32 v38, v40, v41
	v_fmamk_f32 v38, v38, 0x3a000000, v1
	v_mul_f32_e32 v40, 0x4f800000, v38
	v_cmp_gt_f32_e32 vcc, s6, v38
	s_nop 1
	v_cndmask_b32_e32 v38, v38, v40, vcc
	v_sqrt_f32_e32 v40, v38
	s_nop 0
	v_add_u32_e32 v41, -1, v40
	v_add_u32_e32 v42, 1, v40
	v_fma_f32 v43, -v41, v40, v38
	v_fma_f32 v44, -v42, v40, v38
	v_cmp_ge_f32_e64 s[38:39], 0, v43
	s_nop 1
	v_cndmask_b32_e64 v40, v40, v41, s[38:39]
	v_cmp_lt_f32_e64 s[38:39], 0, v44
	s_nop 1
	v_cndmask_b32_e64 v40, v40, v42, s[38:39]
	v_mul_f32_e32 v41, 0x37800000, v40
	v_cndmask_b32_e32 v40, v40, v41, vcc
	v_cmp_class_f32_e32 vcc, v38, v246
	v_lshl_add_u32 v42, v244, 2, 0
	s_nop 0
	v_cndmask_b32_e32 v38, v40, v38, vcc
	v_div_scale_f32 v40, s[6:7], v38, v38, 1.0
	v_rcp_f32_e32 v41, v40
	v_div_scale_f32 v43, vcc, 1.0, v38, 1.0
	v_fma_f32 v44, -v40, v41, 1.0
	v_fmac_f32_e32 v41, v44, v41
	v_mul_f32_e32 v44, v43, v41
	v_fma_f32 v45, -v40, v44, v43
	v_fmac_f32_e32 v44, v45, v41
	v_fma_f32 v40, -v40, v44, v43
	v_div_fmas_f32 v40, v40, v41, v44
	v_div_fixup_f32 v38, v40, v38, 1.0
	v_add_u32_e32 v40, 0x20400, v42
	ds_write_b32 v40, v38
.LBB0_137:
	s_or_b64 exec, exec, s[0:1]
	v_readlane_b32 s0, v252, 12
	s_waitcnt lgkmcnt(0)
	v_mov_b32_e32 v5, v0
	v_readlane_b32 s1, v252, 13
	s_waitcnt lgkmcnt(0)
	s_barrier
	s_andn2_b64 vcc, exec, s[0:1]
	v_readfirstlane_b32 s6, v5
	s_cbranch_vccnz .LBB0_153
	s_ashr_i32 s7, s6, 6
	s_ashr_i32 s8, s6, 8
	s_cmp_eq_u32 s8, 1
	s_cselect_b64 s[0:1], -1, 0
	s_cmp_lg_u32 s8, 1
	s_cbranch_scc1 .LBB0_140
	s_barrier
